# v17 + P10 row phase: shift/scale loads of all 4 column blocks issued up front (fresh VGPRs), counted vmcnt so waits no longer drain the scattered stores
# speedup vs baseline: 1.0013x; 1.0013x over previous
; __device__ __forceinline__ vu4 pack8(const float (&f)[8]) { vu4 w; w.x = pg8::cvt_pk_bf16(f[0], f[1]); w.y = pg8::cvt_pk_bf16(f[2], f[3]); w.z = pg8::cvt_pk_bf16(f[4], f[5]); w.w = pg8::cvt_pk_bf16(f[6], f[7]); return w; }
; template <bool XSRC_BF, bool XDST_BF> ...
;     const int tid = threadIdx.x, lane = tid & 63, wave = __builtin_amdgcn_readfirstlane(tid >> 6);
;     const int G = gridDim.x, niter = (NTOK / 8 + G - 1) / G;
;     ...
;     vu4 nxb[4], nho[4]; float nxf[4][8];
;     ...
;     int rown = ROW_OF(0);
;     if (rown >= 0) ROW_LOAD(rown)
;     for (int it = 0; it < niter; ++it) {
;         const int row = rown; if (row < 0) break;
;         const int b = seq_of_row(row);
;         float xv[4][8]; vu4 hraw[4];
; #pragma unroll
;         for (int j = 0; j < 4; ++j) { if (XSRC_BF) unpack8(nxb[j], xv[j]); else {
; #pragma unroll
;                 for (int e = 0; e < 8; ++e) xv[j][e] = nxf[j][e]; }
;             hraw[j] = nho[j]; }
;         rown = it + 1 < niter ? ROW_OF(it + 1) : -1;
;         if (rown >= 0) ROW_LOAD(rown)
;         if (ho) {
;             float hv[4][8]; float ss = 0.f;
; #pragma unroll
;             for (int j = 0; j < 4; ++j) { unpack8(hraw[j], hv[j]);
; #pragma unroll
;                 for (int e = 0; e < 8; ++e) ss += hv[j][e] * hv[j][e]; }
;             ss = wave_sum(ss);
;             const float r1 = rsqrtf(ss * (1.0f / DM) + EPSN);
; #pragma unroll
;             for (int j = 0; j < 4; ++j) { float gt[8]; load8f(mgate + (size_t)b * 12288 + 8 * lane + 512 * j, gt);
; #pragma unroll
;                 for (int e = 0; e < 8; ++e) xv[j][e] += gt[e] * (hv[j][e] * r1); }
;         }
;         if (x_dst) {
; #pragma unroll
;             for (int j = 0; j < 4; ++j) { if (XDST_BF) *(vu4*)((bf16_t*)x_dst + (size_t)row * DM + 8 * lane + 512 * j) = pack8(xv[j]); else store8f(x_dst + (size_t)row * DM + 8 * lane + 512 * j, xv[j]); }
;         }
;         if (h || ug) {
;             float ss = 0.f;
; #pragma unroll
;             for (int j = 0; j < 4; ++j)
; #pragma unroll
;                 for (int e = 0; e < 8; ++e) ss += xv[j][e] * xv[j][e];
;             ss = wave_sum(ss);
;             const float r2 = rsqrtf(ss * (1.0f / DM) + EPSN);
; #pragma unroll
;             for (int j = 0; j < 4; ++j) { float sh[8], sc[8], o[8]; load8f(mpre + (size_t)b * 12288 + 8 * lane + 512 * j, sh); load8f(mpre + (size_t)b * 12288 + 2048 + 8 * lane + 512 * j, sc);
.LBB0_1093:
.LBB0_1094:
	s_mul_i32 s7, s11, s3
	s_sub_i32 s7, s9, s7
	s_xor_b32 s6, s10, s8
	s_add_i32 s8, s11, 1
	s_sub_i32 s9, s7, s3
	s_cmp_ge_u32 s7, s3
	s_cselect_b32 s8, s8, s11
	s_cselect_b32 s7, s9, s7
	s_add_i32 s9, s8, 1
	s_cmp_ge_u32 s7, s3
	s_cselect_b32 s3, s9, s8
	s_xor_b32 s3, s3, s6
	s_sub_i32 s31, s3, s6
	s_cmp_lt_i32 s31, 1
	s_cselect_b64 s[6:7], -1, 0
	s_xor_b64 s[4:5], s[4:5], -1
	s_or_b64 s[4:5], s[6:7], s[4:5]
	s_mov_b32 s30, 1
	s_and_b64 vcc, exec, s[4:5]
	s_cbranch_vccnz .LBB0_1101
	v_readlane_b32 s4, v254, 8
	v_mov_b32_e32 v67, 0
	v_readlane_b32 s5, v254, 9
	v_lshlrev_b32_e32 v4, 5, v1
	v_mov_b32_e32 v5, v67
	v_lshl_add_u64 v[68:69], s[4:5], 0, v[66:67]
	v_readlane_b32 s4, v254, 4
	v_readlane_b32 s5, v254, 5
	s_add_u32 s33, s82, 0x58000
	v_lshlrev_b32_e32 v2, 3, v1
	v_lshl_add_u64 v[70:71], s[4:5], 0, v[66:67]
	v_lshl_add_u64 v[4:5], s[82:83], 0, v[4:5]
	s_mov_b64 s[4:5], 0x1a000
	v_and_b32_e32 v66, 16, v66
	v_lshrrev_b32_e32 v1, 1, v1
	s_addc_u32 s34, s83, 0
	v_lshl_add_u64 v[72:73], v[4:5], 0, s[4:5]
	v_lshl_add_u64 v[74:75], s[84:85], 0, v[66:67]
	v_mul_u32_u24_e32 v1, 0x500, v1
	s_mov_b32 s3, 0
	s_mov_b64 s[4:5], 0x1000
	s_movk_i32 s35, 0x1000
	s_mov_b64 s[6:7], 0x1800
	v_mov_b32_e32 v84, 0x358637bd
	s_mov_b32 s36, 0x800000
	v_lshlrev_b32_e32 v66, 2, v2
	s_mov_b64 s[8:9], 0x2000
	s_movk_i32 s37, 0x600
	s_mov_b64 s[10:11], 0x3000
	s_movk_i32 s38, 0x3000
	s_mov_b64 s[12:13], 0x3800
	v_mov_b32_e32 v85, 0x8000
	v_mov_b32_e32 v86, 0xc000
	v_mov_b32_e32 v87, 0x3a000000
	s_waitcnt vmcnt(0)
	s_branch .LBB0_1097
.LBB0_1096:
	v_sub_co_u32_e32 v76, vcc, s2, v85
	s_nop 0
	v_readfirstlane_b32 s17, v76
	s_lshr_b32 s17, s17, 12
	s_add_i32 s17, s17, 4
	s_lshr_b32 s39, s2, 13
	s_and_b64 s[26:27], vcc, exec
	s_cselect_b32 s17, s39, s17
	v_lshlrev_b32_e32 v124, 16, v34
	v_and_b32_e32 v125, 0xffff0000, v34
	v_lshlrev_b32_e32 v126, 16, v35
	v_and_b32_e32 v127, 0xffff0000, v35
	v_mad_u64_u32 v[34:35], s[26:27], s17, v86, v[72:73]
	v_lshlrev_b32_e32 v100, 16, v62
	v_and_b32_e32 v101, 0xffff0000, v62
	v_lshlrev_b32_e32 v102, 16, v63
	v_and_b32_e32 v103, 0xffff0000, v63
	v_lshlrev_b32_e32 v104, 16, v64
	v_and_b32_e32 v105, 0xffff0000, v64
	v_lshlrev_b32_e32 v106, 16, v65
	v_and_b32_e32 v107, 0xffff0000, v65
	v_lshlrev_b32_e32 v108, 16, v58
	v_and_b32_e32 v109, 0xffff0000, v58
	v_lshlrev_b32_e32 v110, 16, v59
	v_and_b32_e32 v111, 0xffff0000, v59
	v_lshlrev_b32_e32 v112, 16, v60
	v_and_b32_e32 v113, 0xffff0000, v60
	v_lshlrev_b32_e32 v114, 16, v61
	v_and_b32_e32 v115, 0xffff0000, v61
	v_lshlrev_b32_e32 v116, 16, v54
	v_and_b32_e32 v117, 0xffff0000, v54
	v_lshlrev_b32_e32 v118, 16, v55
	v_and_b32_e32 v119, 0xffff0000, v55
	v_lshlrev_b32_e32 v120, 16, v56
	v_and_b32_e32 v121, 0xffff0000, v56
	v_lshlrev_b32_e32 v122, 16, v57
	v_and_b32_e32 v123, 0xffff0000, v57
	global_load_dwordx4 v[54:57], v[34:35], off offset:16
	global_load_dwordx4 v[58:61], v[34:35], off
	global_load_dwordx4 v[62:65], v[34:35], off offset:2064
	global_load_dwordx4 v[76:79], v[34:35], off offset:2048
	v_add_co_u32_e32 v92, vcc, s35, v34
	v_lshl_add_u64 v[88:89], v[34:35], 0, s[4:5]
	s_nop 0
	v_addc_co_u32_e32 v93, vcc, 0, v35, vcc
	global_load_dwordx4 v[80:83], v[92:93], off
	s_nop 0
	global_load_dwordx4 v[88:91], v[88:89], off offset:16
	v_lshl_add_u64 v[34:35], v[34:35], 0, s[6:7]
	global_load_dwordx4 v[92:95], v[92:93], off offset:2048
	s_nop 0
	global_load_dwordx4 v[96:99], v[34:35], off offset:16
	v_lshlrev_b32_e32 v176, 16, v38
	v_and_b32_e32 v177, 0xffff0000, v38
	v_lshlrev_b32_e32 v172, 16, v39
	v_and_b32_e32 v173, 0xffff0000, v39
	v_pk_mul_f32 v[38:39], v[176:177], v[176:177]
	v_lshlrev_b32_e32 v128, 16, v36
	v_and_b32_e32 v129, 0xffff0000, v36
	v_pk_mul_f32 v[174:175], v[172:173], v[172:173]
	v_add_f32_e32 v36, v38, v39
	v_lshlrev_b32_e32 v170, 16, v40
	v_and_b32_e32 v171, 0xffff0000, v40
	v_add_f32_e32 v36, v174, v36
	v_lshlrev_b32_e32 v166, 16, v41
	v_and_b32_e32 v167, 0xffff0000, v41
	v_pk_mul_f32 v[40:41], v[170:171], v[170:171]
	v_add_f32_e32 v36, v175, v36
	v_add_f32_e32 v36, v40, v36
	v_pk_mul_f32 v[168:169], v[166:167], v[166:167]
	v_add_f32_e32 v36, v41, v36
	v_lshlrev_b32_e32 v164, 16, v42
	v_and_b32_e32 v165, 0xffff0000, v42
	v_add_f32_e32 v36, v168, v36
	v_lshlrev_b32_e32 v160, 16, v43
	v_and_b32_e32 v161, 0xffff0000, v43
	v_pk_mul_f32 v[42:43], v[164:165], v[164:165]
	v_add_f32_e32 v36, v169, v36
	v_add_f32_e32 v36, v42, v36
	v_pk_mul_f32 v[162:163], v[160:161], v[160:161]
	v_add_f32_e32 v36, v43, v36
	v_lshlrev_b32_e32 v158, 16, v44
	v_and_b32_e32 v159, 0xffff0000, v44
	v_add_f32_e32 v36, v162, v36
	v_lshlrev_b32_e32 v154, 16, v45
	v_and_b32_e32 v155, 0xffff0000, v45
	v_pk_mul_f32 v[44:45], v[158:159], v[158:159]
	v_add_f32_e32 v36, v163, v36
	v_add_f32_e32 v36, v44, v36
	v_pk_mul_f32 v[156:157], v[154:155], v[154:155]
	v_add_f32_e32 v36, v45, v36
	v_lshlrev_b32_e32 v152, 16, v46
	v_and_b32_e32 v153, 0xffff0000, v46
	v_add_f32_e32 v36, v156, v36
	v_lshlrev_b32_e32 v148, 16, v47
	v_and_b32_e32 v149, 0xffff0000, v47
	v_pk_mul_f32 v[46:47], v[152:153], v[152:153]
	v_add_f32_e32 v36, v157, v36
	v_add_f32_e32 v36, v46, v36
	v_pk_mul_f32 v[150:151], v[148:149], v[148:149]
	v_add_f32_e32 v36, v47, v36
	v_lshlrev_b32_e32 v146, 16, v48
	v_and_b32_e32 v147, 0xffff0000, v48
	v_add_f32_e32 v36, v150, v36
	v_lshlrev_b32_e32 v142, 16, v49
	v_and_b32_e32 v143, 0xffff0000, v49
	v_pk_mul_f32 v[48:49], v[146:147], v[146:147]
	v_add_f32_e32 v36, v151, v36
	v_add_f32_e32 v36, v48, v36
	v_pk_mul_f32 v[144:145], v[142:143], v[142:143]
	v_add_f32_e32 v36, v49, v36
	v_lshlrev_b32_e32 v140, 16, v50
	v_and_b32_e32 v141, 0xffff0000, v50
	v_add_f32_e32 v36, v144, v36
; __device__ __forceinline__ vu4 pack8(const float (&f)[8]) { vu4 w; w.x = pg8::cvt_pk_bf16(f[0], f[1]); w.y = pg8::cvt_pk_bf16(f[2], f[3]); w.z = pg8::cvt_pk_bf16(f[4], f[5]); w.w = pg8::cvt_pk_bf16(f[6], f[7]); return w; }
; __device__ __forceinline__ float wave_sum(float v) { return lane63(wave_scan_incl(v)); }
; template <bool XSRC_BF, bool XDST_BF> ...
;     ...
;             for (int j = 0; j < 4; ++j) { unpack8(hraw[j], hv[j]);
; #pragma unroll
;                 for (int e = 0; e < 8; ++e) ss += hv[j][e] * hv[j][e]; }
;             ss = wave_sum(ss);
;             const float r1 = rsqrtf(ss * (1.0f / DM) + EPSN);
; #pragma unroll
;             for (int j = 0; j < 4; ++j) { float gt[8]; load8f(mgate + (size_t)b * 12288 + 8 * lane + 512 * j, gt);
; #pragma unroll
;                 for (int e = 0; e < 8; ++e) xv[j][e] += gt[e] * (hv[j][e] * r1); }
;         }
;         if (x_dst) {
; #pragma unroll
;             for (int j = 0; j < 4; ++j) { if (XDST_BF) *(vu4*)((bf16_t*)x_dst + (size_t)row * DM + 8 * lane + 512 * j) = pack8(xv[j]); else store8f(x_dst + (size_t)row * DM + 8 * lane + 512 * j, xv[j]); }
;         }
;         if (h || ug) {
;             float ss = 0.f;
; #pragma unroll
;             for (int j = 0; j < 4; ++j)
; #pragma unroll
;                 for (int e = 0; e < 8; ++e) ss += xv[j][e] * xv[j][e];
;             ss = wave_sum(ss);
;             const float r2 = rsqrtf(ss * (1.0f / DM) + EPSN);
; #pragma unroll
;             for (int j = 0; j < 4; ++j) { float sh[8], sc[8], o[8]; load8f(mpre + (size_t)b * 12288 + 8 * lane + 512 * j, sh); load8f(mpre + (size_t)b * 12288 + 2048 + 8 * lane + 512 * j, sc);
	v_lshlrev_b32_e32 v136, 16, v51
	v_and_b32_e32 v137, 0xffff0000, v51
	v_pk_mul_f32 v[50:51], v[140:141], v[140:141]
	v_add_f32_e32 v36, v145, v36
	v_add_f32_e32 v36, v50, v36
	v_pk_mul_f32 v[138:139], v[136:137], v[136:137]
	v_add_f32_e32 v36, v51, v36
	v_lshlrev_b32_e32 v134, 16, v52
	v_and_b32_e32 v135, 0xffff0000, v52
	v_add_f32_e32 v36, v138, v36
	v_lshlrev_b32_e32 v132, 16, v53
	v_and_b32_e32 v133, 0xffff0000, v53
	v_pk_mul_f32 v[52:53], v[134:135], v[134:135]
	v_add_f32_e32 v36, v139, v36
	v_add_f32_e32 v36, v52, v36
	v_pk_mul_f32 v[34:35], v[132:133], v[132:133]
	v_add_f32_e32 v36, v53, v36
	v_add_f32_e32 v34, v34, v36
	v_add_f32_e32 v34, v35, v34
	v_mov_b32_e32 v35, 0
	v_lshlrev_b32_e32 v130, 16, v37
	v_add_f32_dpp v34, v34, v34 row_shr:1 row_mask:0xf bank_mask:0xf bound_ctrl:1
	v_and_b32_e32 v131, 0xffff0000, v37
	s_mul_hi_u32 s39, s17, 0xc000
	v_add_f32_dpp v34, v34, v34 row_shr:2 row_mask:0xf bank_mask:0xf bound_ctrl:1
	s_mul_i32 s17, s17, 0xc000
	s_nop 0
	v_add_f32_dpp v34, v34, v34 row_shr:4 row_mask:0xf bank_mask:0xf bound_ctrl:1
	s_nop 1
	v_add_f32_dpp v34, v34, v34 row_shr:8 row_mask:0xf bank_mask:0xf bound_ctrl:1
	s_nop 1
	v_mov_b32_dpp v35, v34 row_bcast:15 row_mask:0xa bank_mask:0xf
	v_add_f32_e32 v34, v34, v35
	v_mov_b32_e32 v35, 0
	s_nop 1
	v_mov_b32_dpp v35, v34 row_bcast:31 row_mask:0xc bank_mask:0xf
	v_add_f32_e32 v34, v34, v35
	s_nop 0
	v_readlane_b32 s26, v34, 63
	s_nop 1
	v_fma_f32 v34, s26, v87, v84
	v_mul_f32_e32 v35, 0x4b800000, v34
	v_cmp_gt_f32_e32 vcc, s36, v34
	s_lshl_b64 s[26:27], s[2:3], 12
	s_nop 0
	v_cndmask_b32_e32 v34, v34, v35, vcc
	v_rsq_f32_e32 v34, v34
	s_nop 0
	v_mul_f32_e32 v35, 0x45800000, v34
	v_cndmask_b32_e32 v50, v34, v35, vcc
	v_pk_mul_f32 v[34:35], v[50:51], v[176:177] op_sel_hi:[0,1]
	s_waitcnt vmcnt(6)
	v_pk_fma_f32 v[100:101], v[58:59], v[34:35], v[100:101]
	v_pk_mul_f32 v[34:35], v[50:51], v[172:173] op_sel_hi:[0,1]
	v_pk_fma_f32 v[102:103], v[60:61], v[34:35], v[102:103]
	v_pk_mul_f32 v[34:35], v[50:51], v[170:171] op_sel_hi:[0,1]
	v_pk_fma_f32 v[104:105], v[54:55], v[34:35], v[104:105]
	v_pk_mul_f32 v[34:35], v[50:51], v[166:167] op_sel_hi:[0,1]
	v_pk_fma_f32 v[106:107], v[56:57], v[34:35], v[106:107]
	v_pk_mul_f32 v[34:35], v[50:51], v[164:165] op_sel_hi:[0,1]
	s_waitcnt vmcnt(4)
	v_pk_fma_f32 v[44:45], v[76:77], v[34:35], v[108:109]
	v_pk_mul_f32 v[34:35], v[50:51], v[160:161] op_sel_hi:[0,1]
	v_pk_fma_f32 v[48:49], v[78:79], v[34:35], v[110:111]
	v_pk_mul_f32 v[34:35], v[50:51], v[158:159] op_sel_hi:[0,1]
	v_pk_fma_f32 v[42:43], v[62:63], v[34:35], v[112:113]
	v_pk_mul_f32 v[34:35], v[50:51], v[154:155] op_sel_hi:[0,1]
	v_pk_fma_f32 v[46:47], v[64:65], v[34:35], v[114:115]
	v_pk_mul_f32 v[34:35], v[50:51], v[152:153] op_sel_hi:[0,1]
	v_pk_mul_f32 v[52:53], v[50:51], v[140:141] op_sel_hi:[0,1]
	s_waitcnt vmcnt(3)
	v_pk_fma_f32 v[36:37], v[80:81], v[34:35], v[116:117]
	v_pk_mul_f32 v[34:35], v[50:51], v[148:149] op_sel_hi:[0,1]
	s_waitcnt vmcnt(1)
	v_pk_fma_f32 v[76:77], v[92:93], v[52:53], v[124:125]
	v_pk_mul_f32 v[52:53], v[50:51], v[136:137] op_sel_hi:[0,1]
	v_pk_fma_f32 v[40:41], v[82:83], v[34:35], v[118:119]
	v_pk_mul_f32 v[34:35], v[50:51], v[146:147] op_sel_hi:[0,1]
	v_pk_mul_f32 v[38:39], v[50:51], v[142:143] op_sel_hi:[0,1]
	v_pk_fma_f32 v[78:79], v[94:95], v[52:53], v[126:127]
	v_pk_mul_f32 v[52:53], v[50:51], v[134:135] op_sel_hi:[0,1]
	v_pk_mul_f32 v[50:51], v[50:51], v[132:133] op_sel_hi:[0,1]
	s_waitcnt vmcnt(0)
	v_pk_fma_f32 v[80:81], v[52:53], v[96:97], v[128:129]
	v_pk_fma_f32 v[82:83], v[50:51], v[98:99], v[130:131]
	v_lshl_add_u64 v[54:55], v[68:69], 0, s[26:27]
	v_cvt_pk_bf16_f32 v50, v100, v101
	v_cvt_pk_bf16_f32 v51, v102, v103
	v_cvt_pk_bf16_f32 v52, v104, v105
	v_cvt_pk_bf16_f32 v53, v106, v107
	v_pk_fma_f32 v[34:35], v[88:89], v[34:35], v[120:121]
	v_pk_fma_f32 v[38:39], v[90:91], v[38:39], v[122:123]
	global_store_dwordx4 v[54:55], v[50:53], off
	s_add_u32 s26, s33, s17
	s_addc_u32 s27, s34, s39
	v_cvt_pk_bf16_f32 v50, v44, v45
	v_cvt_pk_bf16_f32 v51, v48, v49
	v_cvt_pk_bf16_f32 v52, v42, v43
	v_cvt_pk_bf16_f32 v53, v46, v47
	global_store_dwordx4 v[54:55], v[50:53], off offset:1024
	v_lshl_add_u64 v[108:109], s[26:27], 0, v[66:67]
	v_add_co_u32_e32 v96, vcc, s38, v108
	v_cvt_pk_bf16_f32 v50, v36, v37
	v_cvt_pk_bf16_f32 v51, v40, v41
	v_cvt_pk_bf16_f32 v52, v34, v35
	v_cvt_pk_bf16_f32 v53, v38, v39
	global_store_dwordx4 v[54:55], v[50:53], off offset:2048
	v_addc_co_u32_e32 v97, vcc, 0, v109, vcc
	s_nop 0
	v_cvt_pk_bf16_f32 v50, v76, v77
	v_cvt_pk_bf16_f32 v51, v78, v79
	v_cvt_pk_bf16_f32 v52, v80, v81
	v_cvt_pk_bf16_f32 v53, v82, v83
	global_store_dwordx4 v[54:55], v[50:53], off offset:3072
	global_load_dwordx4 v[50:53], v66, s[26:27]
	s_nop 0
	global_load_dwordx4 v[54:57], v[96:97], off offset:-4096
	global_load_dwordx4 v[58:61], v66, s[26:27] offset:16
	v_lshl_add_u64 v[88:89], v[108:109], 0, s[8:9]
	global_load_dwordx4 v[62:65], v[88:89], off offset:16
	global_load_dwordx4 v[178:181], v[88:89], off offset:2048
	global_load_dwordx4 v[182:185], v66, s[26:27] offset:2048
	global_load_dwordx4 v[186:189], v66, s[26:27] offset:2064
	global_load_dwordx4 v[190:193], v[88:89], off offset:2064
	v_mov_b32_e32 v232, s35
	v_mov_b32_e32 v233, 0
	v_lshl_add_u64 v[234:235], v[108:109], 0, s[4:5]
	v_lshl_add_u64 v[230:231], v[108:109], 0, v[232:233]
	v_lshl_add_u64 v[236:237], v[108:109], 0, s[10:11]
	v_lshl_add_u64 v[238:239], v[108:109], 0, s[6:7]
	v_lshl_add_u64 v[240:241], v[108:109], 0, s[12:13]
	global_load_dwordx4 v[194:197], v[230:231], off
	global_load_dwordx4 v[198:201], v[96:97], off
	global_load_dwordx4 v[202:205], v[234:235], off offset:16
; __device__ __forceinline__ vu4 pack8(const float (&f)[8]) { vu4 w; w.x = pg8::cvt_pk_bf16(f[0], f[1]); w.y = pg8::cvt_pk_bf16(f[2], f[3]); w.z = pg8::cvt_pk_bf16(f[4], f[5]); w.w = pg8::cvt_pk_bf16(f[6], f[7]); return w; }
; __device__ __forceinline__ float wave_sum(float v) { return lane63(wave_scan_incl(v)); }
; template <bool XSRC_BF, bool XDST_BF> ...
;     ...
;         if (h || ug) {
;             float ss = 0.f;
; #pragma unroll
;             for (int j = 0; j < 4; ++j)
; #pragma unroll
;                 for (int e = 0; e < 8; ++e) ss += xv[j][e] * xv[j][e];
;             ss = wave_sum(ss);
;             const float r2 = rsqrtf(ss * (1.0f / DM) + EPSN);
; #pragma unroll
;             for (int j = 0; j < 4; ++j) { float sh[8], sc[8], o[8]; load8f(mpre + (size_t)b * 12288 + 8 * lane + 512 * j, sh); load8f(mpre + (size_t)b * 12288 + 2048 + 8 * lane + 512 * j, sc);
; #pragma unroll
;                 for (int e = 0; e < 8; ++e) o[e] = xv[j][e] * r2 * sc[e] + sh[e];
;                 if (ug) { const int col = 8 * lane + 512 * j; *(vu4*)(ug + ((size_t)((col >> 4) * 1280 + (row >> 5))) * 768 + (row & 31) * 16 + (col & 8)) = pack8(o); }
;                 else *(vu4*)(h + (size_t)row * DM + 8 * lane + 512 * j) = pack8(o); }
	global_load_dwordx4 v[210:213], v[236:237], off offset:16
	global_load_dwordx4 v[214:217], v[230:231], off offset:2048
	global_load_dwordx4 v[218:221], v[238:239], off offset:16
	global_load_dwordx4 v[222:225], v[96:97], off offset:2048
	global_load_dwordx4 v[226:229], v[240:241], off offset:16
	v_pk_mul_f32 v[90:91], v[100:101], v[100:101]
	v_pk_mul_f32 v[92:93], v[102:103], v[102:103]
	v_add_f32_e32 v90, v90, v91
	v_add_f32_e32 v90, v92, v90
	v_pk_mul_f32 v[94:95], v[104:105], v[104:105]
	v_add_f32_e32 v90, v93, v90
	v_add_f32_e32 v90, v94, v90
	v_pk_mul_f32 v[98:99], v[106:107], v[106:107]
	v_add_f32_e32 v90, v95, v90
	v_add_f32_e32 v90, v98, v90
	v_pk_mul_f32 v[110:111], v[44:45], v[44:45]
	v_add_f32_e32 v90, v99, v90
	v_add_f32_e32 v90, v110, v90
	v_pk_mul_f32 v[112:113], v[48:49], v[48:49]
	v_add_f32_e32 v90, v111, v90
	v_add_f32_e32 v90, v112, v90
	v_pk_mul_f32 v[114:115], v[42:43], v[42:43]
	v_add_f32_e32 v90, v113, v90
	v_add_f32_e32 v90, v114, v90
	v_pk_mul_f32 v[116:117], v[46:47], v[46:47]
	v_add_f32_e32 v90, v115, v90
	v_add_f32_e32 v90, v116, v90
	v_pk_mul_f32 v[118:119], v[36:37], v[36:37]
	v_add_f32_e32 v90, v117, v90
	v_add_f32_e32 v90, v118, v90
	v_pk_mul_f32 v[120:121], v[40:41], v[40:41]
	v_add_f32_e32 v90, v119, v90
	v_add_f32_e32 v90, v120, v90
	v_pk_mul_f32 v[122:123], v[34:35], v[34:35]
	v_add_f32_e32 v90, v121, v90
	v_add_f32_e32 v90, v122, v90
	v_pk_mul_f32 v[124:125], v[38:39], v[38:39]
	v_add_f32_e32 v90, v123, v90
	v_add_f32_e32 v90, v124, v90
	v_pk_mul_f32 v[126:127], v[76:77], v[76:77]
	v_add_f32_e32 v90, v125, v90
	v_add_f32_e32 v90, v126, v90
	v_pk_mul_f32 v[128:129], v[78:79], v[78:79]
	v_add_f32_e32 v90, v127, v90
	v_add_f32_e32 v90, v128, v90
	v_pk_mul_f32 v[130:131], v[80:81], v[80:81]
	v_add_f32_e32 v90, v129, v90
	v_add_f32_e32 v90, v130, v90
	v_pk_mul_f32 v[132:133], v[82:83], v[82:83]
	v_add_f32_e32 v90, v131, v90
	v_add_f32_e32 v90, v132, v90
	v_add_f32_e32 v90, v133, v90
	v_mov_b32_e32 v91, 0
	s_and_b64 s[14:15], s[14:15], s[24:25]
	v_add_f32_dpp v90, v90, v90 row_shr:1 row_mask:0xf bank_mask:0xf bound_ctrl:1
	s_add_i32 s30, s30, 1
	s_nop 0
	v_add_f32_dpp v90, v90, v90 row_shr:2 row_mask:0xf bank_mask:0xf bound_ctrl:1
	s_nop 1
	v_add_f32_dpp v90, v90, v90 row_shr:4 row_mask:0xf bank_mask:0xf bound_ctrl:1
	s_nop 1
	v_add_f32_dpp v90, v90, v90 row_shr:8 row_mask:0xf bank_mask:0xf bound_ctrl:1
	s_nop 1
	v_mov_b32_dpp v91, v90 row_bcast:15 row_mask:0xa bank_mask:0xf
	v_add_f32_e32 v90, v90, v91
	v_mov_b32_e32 v91, 0
	s_nop 1
	v_mov_b32_dpp v91, v90 row_bcast:31 row_mask:0xc bank_mask:0xf
	v_add_f32_e32 v90, v90, v91
	s_nop 0
	v_readlane_b32 s17, v90, 63
	s_nop 1
	v_fma_f32 v90, s17, v87, v84
	v_mul_f32_e32 v91, 0x4b800000, v90
	v_cmp_gt_f32_e32 vcc, s36, v90
	s_lshr_b32 s17, s2, 5
	s_lshl_b32 s2, s2, 5
	v_cndmask_b32_e32 v90, v90, v91, vcc
	v_rsq_f32_e32 v90, v90
	s_and_b32 s2, s2, 0x3e0
	v_lshl_add_u64 v[112:113], v[74:75], 0, s[2:3]
	s_mov_b32 s2, s16
	v_mul_f32_e32 v91, 0x45800000, v90
	v_cndmask_b32_e32 v110, v90, v91, vcc
	v_pk_mul_f32 v[90:91], v[100:101], v[110:111] op_sel_hi:[1,0]
	v_pk_mul_f32 v[44:45], v[44:45], v[110:111] op_sel_hi:[1,0]
	s_waitcnt vmcnt(14)
	v_pk_fma_f32 v[50:51], v[54:55], v[90:91], v[50:51]
	v_pk_mul_f32 v[54:55], v[102:103], v[110:111] op_sel_hi:[1,0]
	v_cvt_pk_bf16_f32 v50, v50, v51
	v_pk_fma_f32 v[52:53], v[56:57], v[54:55], v[52:53]
	v_pk_mul_f32 v[54:55], v[104:105], v[110:111] op_sel_hi:[1,0]
	v_pk_mul_f32 v[56:57], v[106:107], v[110:111] op_sel_hi:[1,0]
	s_waitcnt vmcnt(12)
	v_pk_fma_f32 v[54:55], v[62:63], v[54:55], v[58:59]
	v_pk_fma_f32 v[56:57], v[64:65], v[56:57], v[60:61]
	v_add_u32_e32 v104, s17, v1
	v_cvt_pk_bf16_f32 v51, v52, v53
	v_cvt_pk_bf16_f32 v52, v54, v55
	v_cvt_pk_bf16_f32 v53, v56, v57
	v_mad_u64_u32 v[54:55], s[40:41], v104, s37, v[112:113]
	global_store_dwordx4 v[54:55], v[50:53], off
	s_nop 0
	v_pk_mul_f32 v[42:43], v[42:43], v[110:111] op_sel_hi:[1,0]
	v_pk_mul_f32 v[48:49], v[48:49], v[110:111] op_sel_hi:[1,0]
	v_pk_mul_f32 v[36:37], v[36:37], v[110:111] op_sel_hi:[1,0]
	v_pk_mul_f32 v[34:35], v[34:35], v[110:111] op_sel_hi:[1,0]
	v_pk_mul_f32 v[40:41], v[40:41], v[110:111] op_sel_hi:[1,0]
	s_waitcnt vmcnt(11)
	v_pk_fma_f32 v[44:45], v[44:45], v[178:179], v[182:183]
	v_pk_fma_f32 v[48:49], v[48:49], v[180:181], v[184:185]
	s_waitcnt vmcnt(9)
	v_pk_fma_f32 v[50:51], v[42:43], v[190:191], v[186:187]
	v_pk_mul_f32 v[42:43], v[46:47], v[110:111] op_sel_hi:[1,0]
	v_add_co_u32_e32 v58, vcc, s35, v108
	v_pk_fma_f32 v[46:47], v[42:43], v[192:193], v[188:189]
	v_cvt_pk_bf16_f32 v42, v44, v45
	v_cvt_pk_bf16_f32 v45, v46, v47
	v_add_u32_e32 v46, 0xa000, v104
	v_cvt_pk_bf16_f32 v43, v48, v49
	v_cvt_pk_bf16_f32 v44, v50, v51
	v_mad_u64_u32 v[46:47], s[26:27], v46, s37, v[112:113]
	global_store_dwordx4 v[46:47], v[42:45], off
	v_addc_co_u32_e32 v59, vcc, 0, v109, vcc
	v_lshl_add_u64 v[50:51], v[108:109], 0, s[4:5]
	v_lshl_add_u64 v[54:55], v[108:109], 0, s[10:11]
	v_mov_b64_e32 v[64:65], v[4:5]
	v_mov_b64_e32 v[62:63], v[2:3]
	v_add_u32_e32 v2, 0x1e000, v104
	s_and_b64 vcc, exec, s[14:15]
	v_pk_mul_f32 v[4:5], v[78:79], v[110:111] op_sel_hi:[1,0]
	s_waitcnt vmcnt(8)
	v_pk_fma_f32 v[36:37], v[36:37], v[198:199], v[194:195]
	v_pk_fma_f32 v[40:41], v[40:41], v[200:201], v[196:197]
	v_mov_b64_e32 v[48:49], v[28:29]
	v_mov_b64_e32 v[46:47], v[26:27]
	s_waitcnt vmcnt(6)
	v_pk_fma_f32 v[42:43], v[34:35], v[210:211], v[202:203]
	v_pk_mul_f32 v[34:35], v[38:39], v[110:111] op_sel_hi:[1,0]
	s_nop 0
	v_pk_fma_f32 v[38:39], v[34:35], v[212:213], v[204:205]
	v_cvt_pk_bf16_f32 v34, v36, v37
	v_cvt_pk_bf16_f32 v37, v38, v39
	v_add_u32_e32 v38, 0x14000, v104
	v_cvt_pk_bf16_f32 v35, v40, v41
	v_cvt_pk_bf16_f32 v36, v42, v43
	v_mad_u64_u32 v[38:39], s[26:27], v38, s37, v[112:113]
	global_store_dwordx4 v[38:39], v[34:37], off
	v_mov_b64_e32 v[40:41], v[12:13]
	v_mov_b64_e32 v[38:39], v[10:11]
	v_lshl_add_u64 v[34:35], v[108:109], 0, s[6:7]
	s_nop 0
	v_lshl_add_u64 v[34:35], v[108:109], 0, s[12:13]
	v_mov_b64_e32 v[60:61], v[8:9]
	v_mov_b64_e32 v[58:59], v[6:7]
	v_mad_u64_u32 v[6:7], s[14:15], v2, s37, v[112:113]
	v_pk_mul_f32 v[2:3], v[76:77], v[110:111] op_sel_hi:[1,0]
	v_pk_mul_f32 v[8:9], v[80:81], v[110:111] op_sel_hi:[1,0]
	v_pk_mul_f32 v[10:11], v[82:83], v[110:111] op_sel_hi:[1,0]
	v_mov_b64_e32 v[44:45], v[16:17]
	v_mov_b64_e32 v[52:53], v[32:33]
	v_mov_b64_e32 v[56:57], v[20:21]
	v_mov_b64_e32 v[36:37], v[24:25]
	v_mov_b64_e32 v[42:43], v[14:15]
	v_mov_b64_e32 v[50:51], v[30:31]
	v_mov_b64_e32 v[54:55], v[18:19]
	v_mov_b64_e32 v[34:35], v[22:23]
	s_waitcnt vmcnt(4)
	v_pk_fma_f32 v[2:3], v[2:3], v[222:223], v[214:215]
	v_pk_fma_f32 v[4:5], v[4:5], v[224:225], v[216:217]
	s_waitcnt vmcnt(3)
	v_pk_fma_f32 v[8:9], v[8:9], v[226:227], v[218:219]
	v_pk_fma_f32 v[10:11], v[10:11], v[228:229], v[220:221]
	v_cvt_pk_bf16_f32 v2, v2, v3
	v_cvt_pk_bf16_f32 v3, v4, v5
	v_cvt_pk_bf16_f32 v4, v8, v9
	v_cvt_pk_bf16_f32 v5, v10, v11
	global_store_dwordx4 v[6:7], v[2:5], off
	s_cbranch_vccz .LBB0_1101

; template <bool XSRC_BF, bool XDST_BF> ...
;     ...
;     int rown = ROW_OF(0);
;     if (rown >= 0) ROW_LOAD(rown)
;     for (int it = 0; it < niter; ++it) {
;         const int row = rown; if (row < 0) break;
;         const int b = seq_of_row(row);
;         float xv[4][8]; vu4 hraw[4];
; #pragma unroll
;         for (int j = 0; j < 4; ++j) { if (XSRC_BF) unpack8(nxb[j], xv[j]); else {
; #pragma unroll
;                 for (int e = 0; e < 8; ++e) xv[j][e] = nxf[j][e]; }
;             hraw[j] = nho[j]; }
;         rown = it + 1 < niter ? ROW_OF(it + 1) : -1;
;         if (rown >= 0) ROW_LOAD(rown)
.LBB0_1099:
	s_cmp_gt_i32 s16, -1
	s_waitcnt vmcnt(4)
	v_mov_b64_e32 v[10:11], v[38:39]
	s_waitcnt vmcnt(4)
	v_mov_b64_e32 v[14:15], v[42:43]
	s_waitcnt vmcnt(4)
	v_mov_b64_e32 v[26:27], v[46:47]
	s_waitcnt vmcnt(4)
	v_mov_b64_e32 v[30:31], v[50:51]
	v_mov_b64_e32 v[2:3], v[62:63]
	v_mov_b64_e32 v[6:7], v[58:59]
	v_mov_b64_e32 v[18:19], v[54:55]
	v_mov_b64_e32 v[22:23], v[34:35]
	s_cselect_b64 s[24:25], -1, 0
	s_cmp_lt_i32 s16, 0
	v_mov_b64_e32 v[12:13], v[40:41]
	v_mov_b64_e32 v[16:17], v[44:45]
	v_mov_b64_e32 v[28:29], v[48:49]
	v_mov_b64_e32 v[32:33], v[52:53]
	v_mov_b64_e32 v[4:5], v[64:65]
	v_mov_b64_e32 v[8:9], v[60:61]
	v_mov_b64_e32 v[20:21], v[56:57]
	v_mov_b64_e32 v[24:25], v[36:37]
	s_cbranch_scc1 .LBB0_1096
	s_mov_b32 s17, s3
	s_lshl_b64 s[26:27], s[16:17], 12
	v_lshl_add_u64 v[22:23], v[68:69], 0, s[26:27]
	v_lshl_add_u64 v[30:31], v[70:71], 0, s[26:27]
	global_load_dwordx4 v[2:5], v[22:23], off
	global_load_dwordx4 v[6:9], v[22:23], off offset:1024
	global_load_dwordx4 v[10:13], v[30:31], off
	global_load_dwordx4 v[14:17], v[30:31], off offset:1024
	global_load_dwordx4 v[18:21], v[22:23], off offset:2048
	s_nop 0
	global_load_dwordx4 v[22:25], v[22:23], off offset:3072
	s_nop 0
	global_load_dwordx4 v[26:29], v[30:31], off offset:2048
	s_nop 0
	global_load_dwordx4 v[30:33], v[30:31], off offset:3072
	s_branch .LBB0_1096
